# same as previous but without the static s_setprio for the scan consumer waves (A/B of the priority raise)
# baseline (speedup 1.0000x reference)
.LBB0_384:
	s_or_b64 exec, exec, s[68:69]
	s_lshr_b32 s75, s74, 6
	s_cmpk_gt_u32 s74, 0xff
	s_mov_b64 s[0:1], -1
	s_cbranch_scc0 .LBB0_396
	s_and_b32 s0, s94, 15
	s_lshl_b32 s72, s0, 22
	s_add_i32 s73, s75, -4
	s_cmp_lg_u32 s73, 0
	s_cselect_b64 s[0:1], -1, 0
	s_cmpk_lt_u32 s74, 0x1c0
	s_cselect_b64 s[68:69], -1, 0
	s_not_b32 s70, s75
	s_lshl_b32 s70, s70, 5
	s_and_b32 s87, s70, 32
	s_add_i32 s70, s75, -5
	v_or_b32_e32 v2, s87, v83
	s_cmp_lt_u32 s70, 2
	v_mul_u32_u24_e32 v3, 0x110, v2
	s_cselect_b64 s[70:71], -1, 0
	v_mul_u32_u24_e32 v105, 0x50, v2
	v_lshl_add_u32 v106, s73, 7, v90
	v_lshl_or_b32 v2, s73, 5, v83
	v_lshl_add_u32 v108, s73, 6, v91
	s_add_i32 s73, s87, s95
	s_waitcnt lgkmcnt(0)
	s_barrier
	s_add_i32 s73, s73, s86
	s_waitcnt lgkmcnt(0)
	s_barrier
	s_movk_i32 s88, 0x50
	s_lshl_b32 s73, s73, 1
	v_mul_lo_u32 v107, v2, s88
	s_or_b32 s72, s72, s73
	s_mov_b32 s73, s96
	v_mov_b32_e32 v2, 0
	s_mov_b32 s87, 1
	v_lshl_add_u64 v[80:81], v[78:79], 0, s[72:73]
	v_add_u32_e32 v109, v86, v3
	v_mov_b32_e32 v3, v2
	v_mov_b32_e32 v4, v2
	v_mov_b32_e32 v5, v2
	s_waitcnt vmcnt(0)
	v_mov_b32_e32 v6, v2
	v_mov_b32_e32 v7, v2
	v_mov_b32_e32 v8, v2
	v_mov_b32_e32 v9, v2
	v_mov_b32_e32 v10, v2
	v_mov_b32_e32 v11, v2
	v_mov_b32_e32 v12, v2
	v_mov_b32_e32 v13, v2
	v_mov_b32_e32 v14, v2
	v_mov_b32_e32 v15, v2
	v_mov_b32_e32 v16, v2
	v_mov_b32_e32 v17, v2
	v_mov_b32_e32 v18, v2
	v_mov_b32_e32 v19, v2
	v_mov_b32_e32 v20, v2
	v_mov_b32_e32 v21, v2
	v_mov_b32_e32 v22, v2
	v_mov_b32_e32 v23, v2
	v_mov_b32_e32 v24, v2
	v_mov_b32_e32 v25, v2
	v_mov_b32_e32 v26, v2
	v_mov_b32_e32 v27, v2
	v_mov_b32_e32 v28, v2
	v_mov_b32_e32 v29, v2
	v_mov_b32_e32 v30, v2
	v_mov_b32_e32 v31, v2
	v_mov_b32_e32 v32, v2
	v_mov_b32_e32 v33, v2
	s_and_b64 vcc, exec, s[68:69]
	s_cbranch_vccnz .Lmy_pc0_nosetup
	v_readlane_b32 s98, v255, 3
	v_readlane_b32 s99, v255, 4
	v_readlane_b32 s100, v255, 17
	s_nop 3
	s_lshl_b32 s101, s100, 18
	s_add_u32 s98, s98, s101
	s_addc_u32 s99, s99, 0
	v_lshlrev_b32_e32 v232, 4, v158
	v_mov_b32_e32 v233, 0
	v_lshl_add_u64 v[232:233], s[98:99], 0, v[232:233]
	s_lshl_b32 s101, s100, 17
	s_add_u32 s98, s80, s101
	s_addc_u32 s99, s81, 0
	s_add_u32 s98, s98, 0x34000000
	s_addc_u32 s99, s99, 0
	v_lshlrev_b32_e32 v234, 3, v158
	v_mov_b32_e32 v235, 0
	v_lshl_add_u64 v[234:235], s[98:99], 0, v[234:235]
	v_mov_b32_e32 v236, 0x800
	v_mov_b32_e32 v237, 0
	v_mov_b32_e32 v238, 0x400
	v_mov_b32_e32 v239, 0
	v_mov_b32_e32 v244, 0x100
	v_mov_b32_e32 v245, 0
	v_mov_b32_e32 v202, 0x1000
	v_mov_b32_e32 v203, 0
	v_mov_b32_e32 v195, 0
	global_load_dwordx4 v[224:227], v[232:233], off
	global_load_dwordx4 v[228:231], v[232:233], off offset:1024
	v_lshl_add_u64 v[232:233], v[232:233], 0, v[236:237]

.LBB0_415:
	s_or_b64 exec, exec, s[68:69]
	v_readfirstlane_b32 s88, v0
	s_lshl_b32 s0, s94, 12
	s_lshr_b32 s87, s88, 6
	s_cmpk_gt_u32 s88, 0xff
	s_mov_b64 s[68:69], -1
	s_cbranch_scc0 .LBB0_427
	s_mov_b32 s1, s96
	s_lshl_b64 s[74:75], s[0:1], 10
	s_add_i32 s92, s87, -4
	s_cmp_lg_u32 s92, 0
	s_cselect_b64 s[68:69], -1, 0
	s_cmpk_lt_u32 s88, 0x1c0
	s_cselect_b64 s[70:71], -1, 0
	s_not_b32 s72, s87
	s_lshl_b32 s72, s72, 5
	s_and_b32 s93, s72, 32
	s_add_i32 s72, s87, -5
	v_or_b32_e32 v2, s93, v83
	s_cmp_lt_u32 s72, 2
	v_mul_u32_u24_e32 v3, 0x110, v2
	s_cselect_b64 s[72:73], -1, 0
	v_mul_u32_u24_e32 v105, 0x50, v2
	v_lshl_add_u32 v106, s92, 7, v90
	v_lshl_or_b32 v2, s92, 5, v83
	v_lshl_add_u32 v108, s92, 6, v91
	s_add_i32 s92, s93, s95
	s_add_i32 s92, s92, s86
	s_waitcnt lgkmcnt(0)
	s_barrier
	s_lshl_b32 s86, s92, 1
	s_waitcnt lgkmcnt(0)
	s_barrier
	s_movk_i32 vcc_lo, 0x50
	s_add_u32 s74, s74, s86
	v_mul_lo_u32 v107, v2, vcc_lo
	s_addc_u32 s75, s75, 0
	v_mov_b32_e32 v2, 0
	s_mov_b32 s1, 0
	v_lshl_add_u64 v[80:81], v[76:77], 0, s[74:75]
	s_mov_b64 s[74:75], 0
	v_add_u32_e32 v109, v86, v3
	v_mov_b32_e32 v3, v2
	v_mov_b32_e32 v4, v2
	v_mov_b32_e32 v5, v2
	s_waitcnt vmcnt(0)
	v_mov_b32_e32 v6, v2
	v_mov_b32_e32 v7, v2
	v_mov_b32_e32 v8, v2
	v_mov_b32_e32 v9, v2
	v_mov_b32_e32 v10, v2
	v_mov_b32_e32 v11, v2
	v_mov_b32_e32 v12, v2
	v_mov_b32_e32 v13, v2
	v_mov_b32_e32 v14, v2
	v_mov_b32_e32 v15, v2
	v_mov_b32_e32 v16, v2
	v_mov_b32_e32 v17, v2
	v_mov_b32_e32 v18, v2
	v_mov_b32_e32 v19, v2
	v_mov_b32_e32 v20, v2
	v_mov_b32_e32 v21, v2
	v_mov_b32_e32 v22, v2
	v_mov_b32_e32 v23, v2
	v_mov_b32_e32 v24, v2
	v_mov_b32_e32 v25, v2
	v_mov_b32_e32 v26, v2
	v_mov_b32_e32 v27, v2
	v_mov_b32_e32 v28, v2
	v_mov_b32_e32 v29, v2
	v_mov_b32_e32 v30, v2
	v_mov_b32_e32 v31, v2
	v_mov_b32_e32 v32, v2
	v_mov_b32_e32 v33, v2
	s_and_b64 vcc, exec, s[70:71]
	s_cbranch_vccnz .Lmy_pc1_nosetup
	v_readlane_b32 s98, v255, 3
	v_readlane_b32 s99, v255, 4
	v_readlane_b32 s100, v255, 17
	s_nop 3
	s_lshl_b32 s101, s100, 18
	s_add_u32 s98, s98, s101
	s_addc_u32 s99, s99, 0
	v_lshlrev_b32_e32 v232, 4, v158
	v_mov_b32_e32 v233, 0
	v_lshl_add_u64 v[232:233], s[98:99], 0, v[232:233]
	s_lshl_b32 s101, s100, 17
	s_add_u32 s98, s80, s101
	s_addc_u32 s99, s81, 0
	s_add_u32 s98, s98, 0x34000000
	s_addc_u32 s99, s99, 0
	v_lshlrev_b32_e32 v234, 3, v158
	v_mov_b32_e32 v235, 0
	v_lshl_add_u64 v[234:235], s[98:99], 0, v[234:235]
	v_mov_b32_e32 v236, 0x800
	v_mov_b32_e32 v237, 0
	v_mov_b32_e32 v238, 0x400
	v_mov_b32_e32 v239, 0
	v_mov_b32_e32 v244, 0x100
	v_mov_b32_e32 v245, 0
	v_mov_b32_e32 v202, 0x1000
	v_mov_b32_e32 v203, 0
	v_mov_b32_e32 v195, 0
	global_load_dwordx4 v[224:227], v[232:233], off
	global_load_dwordx4 v[228:231], v[232:233], off offset:1024
	v_lshl_add_u64 v[232:233], v[232:233], 0, v[236:237]
